# write-through publication: P12 split-K partials as sc1 stores/loads (no wbl2/inv in the hand-off); P10 outputs sc1 and the seam after P10 skips the L2 write-back
# baseline (speedup 1.0000x reference)
; __device__ __forceinline__ float fast_sigmoid(float x) { return __builtin_amdgcn_rcpf(1.0f + __expf(-x)); }
; __device__ __forceinline__ bf16x8 pk8(f32x4 a, f32x4 b) { u32x4 w; w.x = cvt_pk_bf16(a[0], a[1]); w.y = cvt_pk_bf16(a[2], a[3]); w.z = cvt_pk_bf16(b[0], b[1]); w.w = cvt_pk_bf16(b[2], b[3]); return __builtin_bit_cast(bf16x8, w); }
;     __device__ __forceinline__ void operator()(const AccT& acc, const pg8::Unit& u, int wr, int wc, int fr, int fq) const {
;     ...
;             for (int m = 0; m < 4; ++m) { const int row = row0 + ai * 128 + m * 16; f32x4 v0, v1;
; #pragma unroll
;                 for (int j = 0; j < 4; ++j) { const float g0 = acc[ai][0][m][0][j], g1 = acc[ai][0][m][1][j];
;                     v0[j] = g0 * fast_sigmoid(g0) * acc[ai][1][m][0][j]; v1[j] = g1 * fast_sigmoid(g1) * acc[ai][1][m][1][j]; }
;                 *(bf16x8*)(hid + (size_t)row * DFF + col0) = pk8(v0, v1); }
.LBB0_1206:
	v_mul_f32_e32 v151, 0xbfb8aa3b, v124
	v_mul_f32_e32 v154, 0xbfb8aa3b, v120
	v_exp_f32_e32 v151, v151
	v_exp_f32_e32 v155, v154
	v_mul_f32_e32 v154, 0xbfb8aa3b, v125
	v_exp_f32_e32 v156, v154
	v_add_f32_e32 v151, 1.0, v151
	v_rcp_f32_e32 v154, v151
	v_add_f32_e32 v151, 1.0, v155
	v_add_f32_e32 v155, 1.0, v156
	v_rcp_f32_e32 v155, v155
	v_mul_f32_e32 v156, 0xbfb8aa3b, v121
	v_exp_f32_e32 v157, v156
	v_rcp_f32_e32 v156, v151
	v_pk_mul_f32 v[124:125], v[124:125], v[154:155]
	v_mul_f32_e32 v151, 0xbfb8aa3b, v127
	v_pk_mul_f32 v[116:117], v[124:125], v[116:117]
	v_add_f32_e32 v124, 1.0, v157
	v_mul_f32_e32 v125, 0xbfb8aa3b, v122
	v_rcp_f32_e32 v157, v124
	v_mul_f32_e32 v124, 0xbfb8aa3b, v126
	v_exp_f32_e32 v125, v125
	v_exp_f32_e32 v124, v124
	v_exp_f32_e32 v151, v151
	v_mul_f32_e32 v154, 0xbfb8aa3b, v123
	v_exp_f32_e32 v155, v154
	v_add_f32_e32 v125, 1.0, v125
	v_add_f32_e32 v124, 1.0, v124
	v_rcp_f32_e32 v154, v125
	v_add_f32_e32 v125, 1.0, v151
	v_rcp_f32_e32 v124, v124
	v_rcp_f32_e32 v125, v125
	v_add_f32_e32 v151, 1.0, v155
	v_rcp_f32_e32 v155, v151
	v_pk_mul_f32 v[120:121], v[120:121], v[156:157]
	v_lshl_or_b32 v152, s60, 7, v146
	v_pk_mul_f32 v[112:113], v[120:121], v[112:113]
	v_pk_mul_f32 v[120:121], v[126:127], v[124:125]
	v_lshl_add_u32 v150, s24, 8, v144
	v_pk_mul_f32 v[118:119], v[120:121], v[118:119]
	v_pk_mul_f32 v[120:121], v[122:123], v[154:155]
	v_ashrrev_i32_e32 v153, 31, v152
	v_pk_mul_f32 v[114:115], v[120:121], v[114:115]
	v_cvt_pk_bf16_f32 v116, v116, v117
	v_cvt_pk_bf16_f32 v117, v118, v119
	v_cvt_pk_bf16_f32 v118, v112, v113
	v_mov_b64_e32 v[112:113], s[8:9]
	v_cvt_pk_bf16_f32 v119, v114, v115
	v_mad_i64_i32 v[120:121], s[26:27], v150, s51, v[112:113]
	v_lshlrev_b64 v[114:115], 1, v[152:153]
	v_lshl_add_u64 v[120:121], v[120:121], 0, v[114:115]
	global_store_dwordx4 v[120:121], v[116:119], off sc1
	s_andn2_b64 vcc, exec, s[0:1]
	s_mov_b64 s[0:1], -1
	v_mul_f32_e32 v116, 0xbfb8aa3b, v108
	v_mul_f32_e32 v117, 0xbfb8aa3b, v104
	v_mul_f32_e32 v118, 0xbfb8aa3b, v109
	v_exp_f32_e32 v116, v116
	v_exp_f32_e32 v117, v117
	v_exp_f32_e32 v118, v118
	v_add_f32_e32 v116, 1.0, v116
	v_add_f32_e32 v119, 1.0, v117
	v_add_f32_e32 v117, 1.0, v118
	v_rcp_f32_e32 v116, v116
	v_rcp_f32_e32 v117, v117
	v_mul_f32_e32 v118, 0xbfb8aa3b, v105
	v_exp_f32_e32 v120, v118
	v_rcp_f32_e32 v118, v119
	v_pk_mul_f32 v[108:109], v[108:109], v[116:117]
	v_mul_f32_e32 v116, 0xbfb8aa3b, v111
	v_pk_mul_f32 v[100:101], v[108:109], v[100:101]
	v_add_f32_e32 v108, 1.0, v120
	v_rcp_f32_e32 v119, v108
	v_mul_f32_e32 v109, 0xbfb8aa3b, v106
	v_mul_f32_e32 v108, 0xbfb8aa3b, v110
	v_exp_f32_e32 v109, v109
	v_exp_f32_e32 v108, v108
	v_exp_f32_e32 v117, v116
	v_mul_f32_e32 v116, 0xbfb8aa3b, v107
	v_pk_mul_f32 v[104:105], v[104:105], v[118:119]
	v_exp_f32_e32 v118, v116
	v_add_f32_e32 v109, 1.0, v109
	v_add_f32_e32 v108, 1.0, v108
	v_rcp_f32_e32 v116, v109
	v_add_f32_e32 v109, 1.0, v117
	v_rcp_f32_e32 v108, v108
	v_rcp_f32_e32 v109, v109
	v_add_f32_e32 v117, 1.0, v118
	v_rcp_f32_e32 v117, v117
	v_pk_mul_f32 v[104:105], v[104:105], v[96:97]
	v_pk_mul_f32 v[96:97], v[110:111], v[108:109]
	v_or_b32_e32 v108, 16, v150
	v_pk_mul_f32 v[102:103], v[96:97], v[102:103]
	v_pk_mul_f32 v[96:97], v[106:107], v[116:117]
	s_nop 0
	v_pk_mul_f32 v[106:107], v[96:97], v[98:99]
	v_cvt_pk_bf16_f32 v96, v100, v101
	v_mad_i64_i32 v[100:101], s[26:27], v108, s51, v[112:113]
	v_cvt_pk_bf16_f32 v97, v102, v103
	v_cvt_pk_bf16_f32 v98, v104, v105
	v_cvt_pk_bf16_f32 v99, v106, v107
	v_lshl_add_u64 v[100:101], v[100:101], 0, v[114:115]
	global_store_dwordx4 v[100:101], v[96:99], off sc1
	s_nop 1
	v_mul_f32_e32 v96, 0xbfb8aa3b, v92
	v_mul_f32_e32 v97, 0xbfb8aa3b, v88
	v_mul_f32_e32 v98, 0xbfb8aa3b, v93
	v_exp_f32_e32 v96, v96
	v_exp_f32_e32 v97, v97
	v_exp_f32_e32 v98, v98
	v_add_f32_e32 v96, 1.0, v96
	v_add_f32_e32 v99, 1.0, v97
	v_add_f32_e32 v97, 1.0, v98
	v_rcp_f32_e32 v96, v96
	v_rcp_f32_e32 v97, v97
	v_mul_f32_e32 v98, 0xbfb8aa3b, v89
	v_exp_f32_e32 v100, v98
	v_rcp_f32_e32 v98, v99
	v_pk_mul_f32 v[92:93], v[92:93], v[96:97]
	v_mul_f32_e32 v96, 0xbfb8aa3b, v95
	v_pk_mul_f32 v[84:85], v[92:93], v[84:85]
	v_add_f32_e32 v92, 1.0, v100
	v_rcp_f32_e32 v99, v92
	v_mul_f32_e32 v93, 0xbfb8aa3b, v90
	v_mul_f32_e32 v92, 0xbfb8aa3b, v94
	v_exp_f32_e32 v93, v93
	v_exp_f32_e32 v92, v92
	v_exp_f32_e32 v97, v96
	v_mul_f32_e32 v96, 0xbfb8aa3b, v91
	v_pk_mul_f32 v[88:89], v[88:89], v[98:99]
	v_exp_f32_e32 v98, v96
	v_add_f32_e32 v93, 1.0, v93
	v_add_f32_e32 v92, 1.0, v92
	v_rcp_f32_e32 v96, v93
	v_add_f32_e32 v93, 1.0, v97
	v_rcp_f32_e32 v92, v92
	v_rcp_f32_e32 v93, v93
	v_add_f32_e32 v97, 1.0, v98
	v_rcp_f32_e32 v97, v97
	v_pk_mul_f32 v[88:89], v[88:89], v[80:81]
	v_pk_mul_f32 v[80:81], v[94:95], v[92:93]
	v_or_b32_e32 v92, 32, v150
	v_pk_mul_f32 v[86:87], v[80:81], v[86:87]
	v_pk_mul_f32 v[80:81], v[90:91], v[96:97]
	s_nop 0
	v_pk_mul_f32 v[90:91], v[80:81], v[82:83]
	v_cvt_pk_bf16_f32 v80, v84, v85
	v_mad_i64_i32 v[84:85], s[26:27], v92, s51, v[112:113]
	v_cvt_pk_bf16_f32 v81, v86, v87
	v_cvt_pk_bf16_f32 v82, v88, v89
	v_cvt_pk_bf16_f32 v83, v90, v91
	v_lshl_add_u64 v[84:85], v[84:85], 0, v[114:115]
	global_store_dwordx4 v[84:85], v[80:83], off sc1
	s_nop 1
	v_mul_f32_e32 v80, 0xbfb8aa3b, v76
	v_mul_f32_e32 v81, 0xbfb8aa3b, v72
	v_mul_f32_e32 v82, 0xbfb8aa3b, v77
	v_exp_f32_e32 v80, v80
	v_exp_f32_e32 v81, v81
	v_exp_f32_e32 v82, v82
	v_add_f32_e32 v80, 1.0, v80
	v_add_f32_e32 v83, 1.0, v81
	v_add_f32_e32 v81, 1.0, v82
	v_rcp_f32_e32 v80, v80
	v_rcp_f32_e32 v81, v81
	v_mul_f32_e32 v82, 0xbfb8aa3b, v73
	v_exp_f32_e32 v84, v82
	v_rcp_f32_e32 v82, v83
	v_pk_mul_f32 v[76:77], v[76:77], v[80:81]
; __device__ __forceinline__ float fast_sigmoid(float x) { return __builtin_amdgcn_rcpf(1.0f + __expf(-x)); }
; __device__ __forceinline__ bf16x8 pk8(f32x4 a, f32x4 b) { u32x4 w; w.x = cvt_pk_bf16(a[0], a[1]); w.y = cvt_pk_bf16(a[2], a[3]); w.z = cvt_pk_bf16(b[0], b[1]); w.w = cvt_pk_bf16(b[2], b[3]); return __builtin_bit_cast(bf16x8, w); }
;     __device__ __forceinline__ void operator()(const AccT& acc, const pg8::Unit& u, int wr, int wc, int fr, int fq) const {
;     ...
;             for (int m = 0; m < 4; ++m) { const int row = row0 + ai * 128 + m * 16; f32x4 v0, v1;
; #pragma unroll
;                 for (int j = 0; j < 4; ++j) { const float g0 = acc[ai][0][m][0][j], g1 = acc[ai][0][m][1][j];
;                     v0[j] = g0 * fast_sigmoid(g0) * acc[ai][1][m][0][j]; v1[j] = g1 * fast_sigmoid(g1) * acc[ai][1][m][1][j]; }
;                 *(bf16x8*)(hid + (size_t)row * DFF + col0) = pk8(v0, v1); }
	v_mul_f32_e32 v80, 0xbfb8aa3b, v79
	v_pk_mul_f32 v[68:69], v[76:77], v[68:69]
	v_add_f32_e32 v76, 1.0, v84
	v_rcp_f32_e32 v83, v76
	v_mul_f32_e32 v77, 0xbfb8aa3b, v74
	v_mul_f32_e32 v76, 0xbfb8aa3b, v78
	v_exp_f32_e32 v77, v77
	v_exp_f32_e32 v76, v76
	v_exp_f32_e32 v81, v80
	v_mul_f32_e32 v80, 0xbfb8aa3b, v75
	v_pk_mul_f32 v[72:73], v[72:73], v[82:83]
	v_exp_f32_e32 v82, v80
	v_add_f32_e32 v77, 1.0, v77
	v_add_f32_e32 v76, 1.0, v76
	v_rcp_f32_e32 v80, v77
	v_add_f32_e32 v77, 1.0, v81
	v_rcp_f32_e32 v76, v76
	v_rcp_f32_e32 v77, v77
	v_add_f32_e32 v81, 1.0, v82
	v_rcp_f32_e32 v81, v81
	v_pk_mul_f32 v[72:73], v[72:73], v[64:65]
	v_pk_mul_f32 v[64:65], v[78:79], v[76:77]
	v_or_b32_e32 v76, 48, v150
	v_pk_mul_f32 v[70:71], v[64:65], v[70:71]
	v_pk_mul_f32 v[64:65], v[74:75], v[80:81]
	s_nop 0
	v_pk_mul_f32 v[74:75], v[64:65], v[66:67]
	v_cvt_pk_bf16_f32 v64, v68, v69
	v_mad_i64_i32 v[68:69], s[26:27], v76, s51, v[112:113]
	v_cvt_pk_bf16_f32 v65, v70, v71
	v_cvt_pk_bf16_f32 v66, v72, v73
	v_cvt_pk_bf16_f32 v67, v74, v75
	v_lshl_add_u64 v[68:69], v[68:69], 0, v[114:115]
	global_store_dwordx4 v[68:69], v[64:67], off sc1
	v_add_u32_e32 v68, 0x80, v150
	s_nop 0
	v_mul_f32_e32 v64, 0xbfb8aa3b, v60
	v_mul_f32_e32 v65, 0xbfb8aa3b, v56
	v_mul_f32_e32 v66, 0xbfb8aa3b, v61
	v_exp_f32_e32 v64, v64
	v_exp_f32_e32 v65, v65
	v_exp_f32_e32 v66, v66
	v_add_f32_e32 v64, 1.0, v64
	v_add_f32_e32 v67, 1.0, v65
	v_add_f32_e32 v65, 1.0, v66
	v_rcp_f32_e32 v64, v64
	v_rcp_f32_e32 v65, v65
	v_mul_f32_e32 v66, 0xbfb8aa3b, v57
	v_exp_f32_e32 v69, v66
	v_rcp_f32_e32 v66, v67
	v_pk_mul_f32 v[60:61], v[60:61], v[64:65]
	v_mul_f32_e32 v64, 0xbfb8aa3b, v63
	v_pk_mul_f32 v[52:53], v[60:61], v[52:53]
	v_add_f32_e32 v60, 1.0, v69
	v_rcp_f32_e32 v67, v60
	v_mul_f32_e32 v61, 0xbfb8aa3b, v58
	v_mul_f32_e32 v60, 0xbfb8aa3b, v62
	v_exp_f32_e32 v61, v61
	v_exp_f32_e32 v60, v60
	v_exp_f32_e32 v65, v64
	v_mul_f32_e32 v64, 0xbfb8aa3b, v59
	v_pk_mul_f32 v[56:57], v[56:57], v[66:67]
	v_exp_f32_e32 v66, v64
	v_add_f32_e32 v61, 1.0, v61
	v_add_f32_e32 v60, 1.0, v60
	v_rcp_f32_e32 v64, v61
	v_add_f32_e32 v61, 1.0, v65
	v_rcp_f32_e32 v60, v60
	v_rcp_f32_e32 v61, v61
	v_add_f32_e32 v65, 1.0, v66
	v_rcp_f32_e32 v65, v65
	v_pk_mul_f32 v[56:57], v[56:57], v[48:49]
	v_pk_mul_f32 v[48:49], v[62:63], v[60:61]
	s_nop 0
	v_pk_mul_f32 v[54:55], v[48:49], v[54:55]
	v_pk_mul_f32 v[48:49], v[58:59], v[64:65]
	s_nop 0
	v_pk_mul_f32 v[58:59], v[48:49], v[50:51]
	v_cvt_pk_bf16_f32 v48, v52, v53
	v_mad_i64_i32 v[52:53], s[26:27], v68, s51, v[112:113]
	v_cvt_pk_bf16_f32 v49, v54, v55
	v_cvt_pk_bf16_f32 v50, v56, v57
	v_cvt_pk_bf16_f32 v51, v58, v59
	v_lshl_add_u64 v[52:53], v[52:53], 0, v[114:115]
	global_store_dwordx4 v[52:53], v[48:51], off sc1
	s_nop 1
	v_mul_f32_e32 v48, 0xbfb8aa3b, v44
	v_mul_f32_e32 v49, 0xbfb8aa3b, v40
	v_mul_f32_e32 v50, 0xbfb8aa3b, v45
	v_exp_f32_e32 v48, v48
	v_exp_f32_e32 v49, v49
	v_exp_f32_e32 v50, v50
	v_add_f32_e32 v48, 1.0, v48
	v_add_f32_e32 v51, 1.0, v49
	v_add_f32_e32 v49, 1.0, v50
	v_rcp_f32_e32 v48, v48
	v_rcp_f32_e32 v49, v49
	v_mul_f32_e32 v50, 0xbfb8aa3b, v41
	v_exp_f32_e32 v52, v50
	v_rcp_f32_e32 v50, v51
	v_pk_mul_f32 v[44:45], v[44:45], v[48:49]
	v_mul_f32_e32 v48, 0xbfb8aa3b, v47
	v_pk_mul_f32 v[36:37], v[44:45], v[36:37]
	v_add_f32_e32 v44, 1.0, v52
	v_rcp_f32_e32 v51, v44
	v_mul_f32_e32 v45, 0xbfb8aa3b, v42
	v_mul_f32_e32 v44, 0xbfb8aa3b, v46
	v_exp_f32_e32 v45, v45
	v_exp_f32_e32 v44, v44
	v_exp_f32_e32 v49, v48
	v_mul_f32_e32 v48, 0xbfb8aa3b, v43
	v_pk_mul_f32 v[40:41], v[40:41], v[50:51]
	v_exp_f32_e32 v50, v48
	v_add_f32_e32 v45, 1.0, v45
	v_add_f32_e32 v44, 1.0, v44
	v_rcp_f32_e32 v48, v45
	v_add_f32_e32 v45, 1.0, v49
	v_rcp_f32_e32 v44, v44
	v_rcp_f32_e32 v45, v45
	v_add_f32_e32 v49, 1.0, v50
	v_rcp_f32_e32 v49, v49
; __device__ __forceinline__ float fast_sigmoid(float x) { return __builtin_amdgcn_rcpf(1.0f + __expf(-x)); }
; __device__ __forceinline__ bf16x8 pk8(f32x4 a, f32x4 b) { u32x4 w; w.x = cvt_pk_bf16(a[0], a[1]); w.y = cvt_pk_bf16(a[2], a[3]); w.z = cvt_pk_bf16(b[0], b[1]); w.w = cvt_pk_bf16(b[2], b[3]); return __builtin_bit_cast(bf16x8, w); }
; #define PG8_BAR __builtin_amdgcn_s_barrier()
; template <class Epi, class Sched, bool ALIGN_EPI = false, bool SP2 = false>
; __device__ __forceinline__ void gemm_phase(PG8_LAS unsigned char* lds, const Gemm g, const Sched& S, const Epi& E) {
;     ...
;         if constexpr (ALIGN_EPI) { if (wr == 1) PG8_BAR; }
;     __device__ __forceinline__ void operator()(const AccT& acc, const pg8::Unit& u, int wr, int wc, int fr, int fq) const {
;     ...
;             for (int m = 0; m < 4; ++m) { const int row = row0 + ai * 128 + m * 16; f32x4 v0, v1;
; #pragma unroll
;                 for (int j = 0; j < 4; ++j) { const float g0 = acc[ai][0][m][0][j], g1 = acc[ai][0][m][1][j];
;                     v0[j] = g0 * fast_sigmoid(g0) * acc[ai][1][m][0][j]; v1[j] = g1 * fast_sigmoid(g1) * acc[ai][1][m][1][j]; }
;                 *(bf16x8*)(hid + (size_t)row * DFF + col0) = pk8(v0, v1); }
	v_pk_mul_f32 v[40:41], v[40:41], v[32:33]
	v_pk_mul_f32 v[32:33], v[46:47], v[44:45]
	v_add_u32_e32 v44, 0x90, v150
	v_pk_mul_f32 v[38:39], v[32:33], v[38:39]
	v_pk_mul_f32 v[32:33], v[42:43], v[48:49]
	s_nop 0
	v_pk_mul_f32 v[42:43], v[32:33], v[34:35]
	v_cvt_pk_bf16_f32 v32, v36, v37
	v_mad_i64_i32 v[36:37], s[26:27], v44, s51, v[112:113]
	v_cvt_pk_bf16_f32 v33, v38, v39
	v_cvt_pk_bf16_f32 v34, v40, v41
	v_cvt_pk_bf16_f32 v35, v42, v43
	v_lshl_add_u64 v[36:37], v[36:37], 0, v[114:115]
	global_store_dwordx4 v[36:37], v[32:35], off sc1
	s_nop 1
	v_mul_f32_e32 v32, 0xbfb8aa3b, v28
	v_mul_f32_e32 v33, 0xbfb8aa3b, v24
	v_mul_f32_e32 v34, 0xbfb8aa3b, v29
	v_exp_f32_e32 v32, v32
	v_exp_f32_e32 v33, v33
	v_exp_f32_e32 v34, v34
	v_add_f32_e32 v32, 1.0, v32
	v_add_f32_e32 v35, 1.0, v33
	v_add_f32_e32 v33, 1.0, v34
	v_rcp_f32_e32 v32, v32
	v_rcp_f32_e32 v33, v33
	v_mul_f32_e32 v34, 0xbfb8aa3b, v25
	v_exp_f32_e32 v36, v34
	v_rcp_f32_e32 v34, v35
	v_pk_mul_f32 v[28:29], v[28:29], v[32:33]
	v_mul_f32_e32 v32, 0xbfb8aa3b, v31
	v_pk_mul_f32 v[20:21], v[28:29], v[20:21]
	v_add_f32_e32 v28, 1.0, v36
	v_rcp_f32_e32 v35, v28
	v_mul_f32_e32 v29, 0xbfb8aa3b, v26
	v_mul_f32_e32 v28, 0xbfb8aa3b, v30
	v_exp_f32_e32 v29, v29
	v_exp_f32_e32 v28, v28
	v_exp_f32_e32 v33, v32
	v_mul_f32_e32 v32, 0xbfb8aa3b, v27
	v_pk_mul_f32 v[24:25], v[24:25], v[34:35]
	v_exp_f32_e32 v34, v32
	v_add_f32_e32 v29, 1.0, v29
	v_add_f32_e32 v28, 1.0, v28
	v_rcp_f32_e32 v32, v29
	v_add_f32_e32 v29, 1.0, v33
	v_rcp_f32_e32 v28, v28
	v_rcp_f32_e32 v29, v29
	v_add_f32_e32 v33, 1.0, v34
	v_rcp_f32_e32 v33, v33
	v_pk_mul_f32 v[24:25], v[24:25], v[16:17]
	v_pk_mul_f32 v[16:17], v[30:31], v[28:29]
	v_add_u32_e32 v28, 0xa0, v150
	v_pk_mul_f32 v[22:23], v[16:17], v[22:23]
	v_pk_mul_f32 v[16:17], v[26:27], v[32:33]
	s_nop 0
	v_pk_mul_f32 v[26:27], v[16:17], v[18:19]
	v_cvt_pk_bf16_f32 v16, v20, v21
	v_mad_i64_i32 v[20:21], s[26:27], v28, s51, v[112:113]
	v_cvt_pk_bf16_f32 v17, v22, v23
	v_cvt_pk_bf16_f32 v18, v24, v25
	v_cvt_pk_bf16_f32 v19, v26, v27
	v_lshl_add_u64 v[20:21], v[20:21], 0, v[114:115]
	global_store_dwordx4 v[20:21], v[16:19], off sc1
	s_nop 1
	v_mul_f32_e32 v16, 0xbfb8aa3b, v12
	v_mul_f32_e32 v17, 0xbfb8aa3b, v8
	v_mul_f32_e32 v18, 0xbfb8aa3b, v13
	v_exp_f32_e32 v16, v16
	v_exp_f32_e32 v17, v17
	v_exp_f32_e32 v18, v18
	v_add_f32_e32 v16, 1.0, v16
	v_add_f32_e32 v19, 1.0, v17
	v_add_f32_e32 v17, 1.0, v18
	v_rcp_f32_e32 v16, v16
	v_rcp_f32_e32 v17, v17
	v_mul_f32_e32 v18, 0xbfb8aa3b, v9
	v_exp_f32_e32 v20, v18
	v_rcp_f32_e32 v18, v19
	v_pk_mul_f32 v[12:13], v[12:13], v[16:17]
	v_mul_f32_e32 v16, 0xbfb8aa3b, v15
	v_pk_mul_f32 v[4:5], v[12:13], v[4:5]
	v_add_f32_e32 v12, 1.0, v20
	v_rcp_f32_e32 v19, v12
	v_mul_f32_e32 v13, 0xbfb8aa3b, v10
	v_mul_f32_e32 v12, 0xbfb8aa3b, v14
	v_exp_f32_e32 v13, v13
	v_exp_f32_e32 v12, v12
	v_exp_f32_e32 v17, v16
	v_mul_f32_e32 v16, 0xbfb8aa3b, v11
	v_pk_mul_f32 v[8:9], v[8:9], v[18:19]
	v_exp_f32_e32 v18, v16
	v_add_f32_e32 v13, 1.0, v13
	v_add_f32_e32 v12, 1.0, v12
	v_rcp_f32_e32 v16, v13
	v_add_f32_e32 v13, 1.0, v17
	v_rcp_f32_e32 v12, v12
	v_rcp_f32_e32 v13, v13
	v_add_f32_e32 v17, 1.0, v18
	v_rcp_f32_e32 v17, v17
	v_pk_mul_f32 v[8:9], v[8:9], v[0:1]
	v_pk_mul_f32 v[0:1], v[14:15], v[12:13]
	v_add_u32_e32 v12, 0xb0, v150
	v_pk_mul_f32 v[6:7], v[0:1], v[6:7]
	v_pk_mul_f32 v[0:1], v[10:11], v[16:17]
	s_nop 0
	v_pk_mul_f32 v[10:11], v[0:1], v[2:3]
	v_cvt_pk_bf16_f32 v0, v4, v5
	v_mad_i64_i32 v[4:5], s[26:27], v12, s51, v[112:113]
	v_cvt_pk_bf16_f32 v1, v6, v7
	v_cvt_pk_bf16_f32 v2, v8, v9
	v_cvt_pk_bf16_f32 v3, v10, v11
	v_lshl_add_u64 v[4:5], v[4:5], 0, v[114:115]
	global_store_dwordx4 v[4:5], v[0:3], off sc1
	s_cbranch_vccnz .LBB0_1199
	s_andn2_b64 vcc, exec, s[6:7]
	s_cbranch_vccnz .LBB0_1198
	s_barrier
	s_branch .LBB0_1198

; __device__ __forceinline__ unsigned xb_add(unsigned* p, unsigned v) { return __hip_atomic_fetch_add(p, v, __ATOMIC_RELAXED, __HIP_MEMORY_SCOPE_AGENT); }
; __device__ __forceinline__ void xcd_barrier(const XcdBarrier& b) {
;     asm volatile("s_waitcnt vmcnt(0)" ::: "memory");
;     __syncthreads();
;     if (threadIdx.x == 0) {
;         unsigned* bar = b.bar;
;         __builtin_amdgcn_s_waitcnt(0);
;         unsigned nloc = b.st[0], nx = b.st[1];
;         if (nloc == 0u) { xcd_barrier_complete(bar, b.x, nloc, nx); b.st[0] = nloc; b.st[1] = nx; }
;         const unsigned old = xb_add(&bar[XB_XSUB(b.x)], 1u);
;         const unsigned gen = old / nloc;
;         if (old + 1u == (gen + 1u) * nloc) {
;             __builtin_amdgcn_fence(__ATOMIC_RELEASE, "agent");
;             asm volatile("s_waitcnt vmcnt(0)" ::: "memory");
;             const unsigned og = xb_add(&bar[XB_TOP], 1u);
.LBB0_1210:
	s_cmp_lt_i32 s56, 12
	s_cselect_b64 s[10:11], -1, 0
	s_cmp_gt_i32 s57, 11
	s_cselect_b64 s[0:1], -1, 0
	s_and_b64 s[0:1], s[10:11], s[0:1]
	s_andn2_b64 vcc, exec, s[0:1]
	s_cbranch_vccnz .LBB0_1307
	s_andn2_b64 vcc, exec, s[4:5]
	s_cbranch_vccnz .LBB0_1265
	s_getreg_b32 s3, hwreg(HW_REG_XCC_ID, 0, 4)
	s_waitcnt vmcnt(0)
	v_cmp_eq_u32_e32 vcc, 0, v178
	s_waitcnt vmcnt(0) lgkmcnt(0)
	s_barrier
	s_and_saveexec_b64 s[0:1], vcc
	s_cbranch_execz .LBB0_1264
	buffer_inv sc1
	v_mov_b32_e32 v0, 0x23ff0
	ds_read2_b32 v[0:1], v0 offset1:1
	s_and_b32 s98, s3, 15
	s_lshl_b32 s98, s98, 8
	s_add_u32 s98, s54, s98
	s_addc_u32 s99, s55, 0
	s_add_u32 s98, s98, 0x22a3400
	s_addc_u32 s99, s99, 0
	v_mov_b32_e32 v2, 0
	v_mov_b32_e32 v3, 1
	global_atomic_add v4, v2, v3, s[98:99] sc0
	s_add_u32 s100, s54, 0x22a5400
	s_addc_u32 s101, s55, 0
	s_waitcnt vmcnt(0) lgkmcnt(0)
	v_mul_u32_u24_e32 v0, 10, v0
	v_mul_u32_u24_e32 v1, 10, v1
	v_add_u32_e32 v4, 1, v4
	v_cmp_eq_u32_e32 vcc, v4, v0
	s_cbranch_vccz .Lxb_poll_s9
	global_atomic_add v2, v3, s[100:101]

; #define PG8_STAGE(bufoff, gbase, voff) do { _Pragma("unroll") for (int _i = 0; _i < 2; ++_i) \
;         __builtin_amdgcn_global_load_lds((const unsigned*)((const char*)(gbase) + (voff)[_i]), (PG8_LAS unsigned*)(lds + (bufoff) + ldsw + _i * 8192), 16, 0, 0); } while (0)
; #define PG8_LDA(dst, b, h) do { _Pragma("unroll") for (int m = 0; m < 4; ++m) _Pragma("unroll") for (int k = 0; k < 2; ++k) dst[m][k] = *(const PG8_LAS bf16x8*)(lds + PG8_SA(b, h) + aoff + m * 2048 + k * 1024); } while (0)
; #define PG8_LDB(dst, b, h) do { _Pragma("unroll") for (int n = 0; n < 2; ++n) _Pragma("unroll") for (int k = 0; k < 2; ++k) dst[n][k] = *(const PG8_LAS bf16x8*)(lds + PG8_SB(b, h) + boff + n * 2048 + k * 1024); } while (0)
; #define PG8_MMA(ai, bj, At, Bt) do { __builtin_amdgcn_s_setprio(1); _Pragma("unroll") for (int m = 0; m < 4; ++m) _Pragma("unroll") for (int n = 0; n < 2; ++n) _Pragma("unroll") for (int k = 0; k < 2; ++k) \
;         acc[ai][bj][m][n] = __builtin_amdgcn_mfma_f32_16x16x32_bf16(Bt[n][k], At[m][k], acc[ai][bj][m][n], 0, 0, 0); __builtin_amdgcn_s_setprio(0); } while (0)
; #define PG8_WAIT_V(n) asm volatile("s_waitcnt vmcnt(" #n ")" ::: "memory")
; template <class Epi, class Sched, bool ALIGN_EPI = false, bool SP2 = false>
; __device__ __forceinline__ void gemm_phase(PG8_LAS unsigned char* lds, const Gemm g, const Sched& S, const Epi& E) {
;     ...
;             PG8_LDB(B0, 0, 0); PG8_LDB(B1, 0, 1); PG8_SCHED; PG8_LDA(At, 0, 0); PG8_STAGE(PG8_SA(1, 1), a1 + hstep, voffA);
;             PG8_WAIT_V(8); PG8_WAIT_L(0); PG8_BAR; PG8_MMA(0, 0, At, B0); PG8_MMA(0, 1, At, B1); PG8_BAR; PG8_SCHED;
;             PG8_LDA(At, 0, 1); PG8_STAGE(PG8_SB(0, 0), b2, voffB); PG8_STAGE(PG8_SB(0, 1), b2 + hstep, voffB); PG8_STAGE(PG8_SA(0, 0), a2, voffA);
;             PG8_WAIT_V(8); PG8_WAIT_L(0); PG8_BAR; PG8_MMA(1, 0, At, B0); PG8_MMA(1, 1, At, B1); PG8_BAR; PG8_SCHED;
;             PG8_LDB(B0, 1, 0); PG8_LDB(B1, 1, 1); PG8_SCHED; PG8_LDA(At, 1, 0); PG8_STAGE(PG8_SA(0, 1), a2 + hstep, voffA);
;             PG8_WAIT_V(8); PG8_WAIT_L(0); PG8_BAR; PG8_MMA(0, 0, At, B0); PG8_MMA(0, 1, At, B1); PG8_BAR; PG8_SCHED;
;             PG8_LDA(At, 1, 1); PG8_STAGE(PG8_SB(1, 0), b3, voffB); PG8_STAGE(PG8_SB(1, 1), b3 + hstep, voffB); PG8_STAGE(PG8_SA(1, 0), a3, voffA);
;             PG8_WAIT_V(8); PG8_WAIT_L(0); PG8_BAR; PG8_MMA(1, 0, At, B0); PG8_MMA(1, 1, At, B1); PG8_BAR; PG8_SCHED;
.LBB0_1440:
	ds_read_b128 v[136:139], v143
	ds_read_b128 v[148:151], v143 offset:1024
	ds_read_b128 v[152:155], v143 offset:2048
	ds_read_b128 v[156:159], v143 offset:3072
	ds_read_b128 v[160:163], v144
	ds_read_b128 v[164:167], v144 offset:1024
	ds_read_b128 v[168:171], v144 offset:2048
	ds_read_b128 v[172:175], v144 offset:3072
	s_add_u32 s3, s22, 0xfff50080
	s_addc_u32 s24, s23, -1
	s_cmp_eq_u32 s51, 18
	s_cselect_b32 s27, s21, s24
	s_cselect_b32 s26, s20, s3
	s_cselect_b32 s25, s5, s50
	s_cselect_b32 s24, s4, s49
	v_lshl_add_u64 v[212:213], s[22:23], 0, v[132:133]
	s_add_i32 m0, s37, 0xc000
	ds_read_b128 v[180:183], v145
	ds_read_b128 v[184:187], v145 offset:1024
	ds_read_b128 v[188:191], v145 offset:2048
	ds_read_b128 v[192:195], v145 offset:3072
	ds_read_b128 v[196:199], v145 offset:4096
	ds_read_b128 v[200:203], v145 offset:5120
	ds_read_b128 v[204:207], v145 offset:6144
	ds_read_b128 v[208:211], v145 offset:7168
	global_load_lds_dwordx4 v[212:213], off
	v_lshl_add_u64 v[212:213], s[22:23], 0, v[134:135]
	s_add_i32 m0, s37, 0xe000
	s_nop 0
	global_load_lds_dwordx4 v[212:213], off
	s_waitcnt vmcnt(8)
	s_waitcnt lgkmcnt(0)
	s_barrier
	s_setprio 1
	s_waitcnt lgkmcnt(0)
	v_mfma_f32_16x16x32_bf16 v[124:127], v[136:139], v[180:183], v[124:127]
	v_mfma_f32_16x16x32_bf16 v[120:123], v[152:155], v[180:183], v[120:123]
	v_mfma_f32_16x16x32_bf16 v[112:115], v[136:139], v[188:191], v[112:115]
	v_mfma_f32_16x16x32_bf16 v[104:107], v[152:155], v[188:191], v[104:107]
	v_mfma_f32_16x16x32_bf16 v[96:99], v[136:139], v[196:199], v[96:99]
	v_mfma_f32_16x16x32_bf16 v[88:91], v[152:155], v[196:199], v[88:91]
	v_mfma_f32_16x16x32_bf16 v[80:83], v[136:139], v[204:207], v[80:83]
	v_mfma_f32_16x16x32_bf16 v[72:75], v[152:155], v[204:207], v[72:75]
	v_mfma_f32_16x16x32_bf16 v[124:127], v[148:151], v[184:187], v[124:127]
	v_mfma_f32_16x16x32_bf16 v[120:123], v[156:159], v[184:187], v[120:123]
	v_mfma_f32_16x16x32_bf16 v[112:115], v[148:151], v[192:195], v[112:115]
	v_mfma_f32_16x16x32_bf16 v[104:107], v[156:159], v[192:195], v[104:107]
	v_mfma_f32_16x16x32_bf16 v[96:99], v[148:151], v[200:203], v[96:99]
	v_mfma_f32_16x16x32_bf16 v[88:91], v[156:159], v[200:203], v[88:91]
	v_mfma_f32_16x16x32_bf16 v[80:83], v[148:151], v[208:211], v[80:83]
	v_mfma_f32_16x16x32_bf16 v[72:75], v[156:159], v[208:211], v[72:75]
	s_setprio 0
	s_setprio 1
	v_mfma_f32_16x16x32_bf16 v[116:119], v[160:163], v[180:183], v[116:119]
	v_mfma_f32_16x16x32_bf16 v[108:111], v[168:171], v[180:183], v[108:111]
	v_mfma_f32_16x16x32_bf16 v[100:103], v[160:163], v[188:191], v[100:103]
	v_mfma_f32_16x16x32_bf16 v[92:95], v[168:171], v[188:191], v[92:95]
	v_mfma_f32_16x16x32_bf16 v[84:87], v[160:163], v[196:199], v[84:87]
	v_mfma_f32_16x16x32_bf16 v[76:79], v[168:171], v[196:199], v[76:79]
	v_mfma_f32_16x16x32_bf16 v[68:71], v[160:163], v[204:207], v[68:71]
	v_mfma_f32_16x16x32_bf16 v[64:67], v[168:171], v[204:207], v[64:67]
	v_mfma_f32_16x16x32_bf16 v[116:119], v[164:167], v[184:187], v[116:119]
	v_mfma_f32_16x16x32_bf16 v[108:111], v[172:175], v[184:187], v[108:111]
	v_mfma_f32_16x16x32_bf16 v[100:103], v[164:167], v[192:195], v[100:103]
	v_mfma_f32_16x16x32_bf16 v[92:95], v[172:175], v[192:195], v[92:95]
	v_mfma_f32_16x16x32_bf16 v[84:87], v[164:167], v[200:203], v[84:87]
	v_mfma_f32_16x16x32_bf16 v[76:79], v[172:175], v[200:203], v[76:79]
	v_mfma_f32_16x16x32_bf16 v[68:71], v[164:167], v[208:211], v[68:71]
	v_mfma_f32_16x16x32_bf16 v[64:67], v[172:175], v[208:211], v[64:67]
	s_setprio 0
	s_barrier
	s_add_i32 s3, s43, s36
	v_lshl_add_u64 v[212:213], s[24:25], 0, v[128:129]
	s_mov_b32 m0, s3
	ds_read_b128 v[180:183], v145 offset:16384
	ds_read_b128 v[184:187], v145 offset:17408
	ds_read_b128 v[188:191], v145 offset:18432
	ds_read_b128 v[192:195], v145 offset:19456
	ds_read_b128 v[196:199], v145 offset:20480
	ds_read_b128 v[200:203], v145 offset:21504
	ds_read_b128 v[204:207], v145 offset:22528
	ds_read_b128 v[208:211], v145 offset:23552
	global_load_lds_dwordx4 v[212:213], off
	s_add_i32 m0, s3, 0x2000
	s_add_u32 s60, s24, 0xb0000
	v_lshl_add_u64 v[214:215], s[24:25], 0, v[130:131]
	s_addc_u32 s61, s25, 0
	s_add_i32 s3, s44, s36
	global_load_lds_dwordx4 v[214:215], off
	v_lshl_add_u64 v[216:217], s[60:61], 0, v[128:129]
	s_mov_b32 m0, s3
	v_lshl_add_u64 v[218:219], s[26:27], 0, v[130:131]
	global_load_lds_dwordx4 v[216:217], off
	v_lshl_add_u64 v[216:217], s[60:61], 0, v[130:131]
	s_add_i32 m0, s3, 0x2000
	s_nop 0
	global_load_lds_dwordx4 v[216:217], off
	v_lshl_add_u64 v[216:217], s[26:27], 0, v[128:129]
	s_mov_b32 m0, s37
	s_nop 0
	global_load_lds_dwordx4 v[216:217], off
	s_mov_b32 m0, s38
	s_nop 0
	global_load_lds_dwordx4 v[218:219], off
	s_waitcnt vmcnt(8)
	s_waitcnt lgkmcnt(0)
	s_barrier
; #define PG8_STAGE(bufoff, gbase, voff) do { _Pragma("unroll") for (int _i = 0; _i < 2; ++_i) \
;         __builtin_amdgcn_global_load_lds((const unsigned*)((const char*)(gbase) + (voff)[_i]), (PG8_LAS unsigned*)(lds + (bufoff) + ldsw + _i * 8192), 16, 0, 0); } while (0)
; #define PG8_LDA(dst, b, h) do { _Pragma("unroll") for (int m = 0; m < 4; ++m) _Pragma("unroll") for (int k = 0; k < 2; ++k) dst[m][k] = *(const PG8_LAS bf16x8*)(lds + PG8_SA(b, h) + aoff + m * 2048 + k * 1024); } while (0)
; #define PG8_LDB(dst, b, h) do { _Pragma("unroll") for (int n = 0; n < 2; ++n) _Pragma("unroll") for (int k = 0; k < 2; ++k) dst[n][k] = *(const PG8_LAS bf16x8*)(lds + PG8_SB(b, h) + boff + n * 2048 + k * 1024); } while (0)
; #define PG8_MMA(ai, bj, At, Bt) do { __builtin_amdgcn_s_setprio(1); _Pragma("unroll") for (int m = 0; m < 4; ++m) _Pragma("unroll") for (int n = 0; n < 2; ++n) _Pragma("unroll") for (int k = 0; k < 2; ++k) \
;         acc[ai][bj][m][n] = __builtin_amdgcn_mfma_f32_16x16x32_bf16(Bt[n][k], At[m][k], acc[ai][bj][m][n], 0, 0, 0); __builtin_amdgcn_s_setprio(0); } while (0)
; #define PG8_WAIT_V(n) asm volatile("s_waitcnt vmcnt(" #n ")" ::: "memory")
; template <class Epi, class Sched, bool ALIGN_EPI = false, bool SP2 = false>
; __device__ __forceinline__ void gemm_phase(PG8_LAS unsigned char* lds, const Gemm g, const Sched& S, const Epi& E) {
;     ...
;             PG8_LDB(B0, 0, 0); PG8_LDB(B1, 0, 1); PG8_SCHED; PG8_LDA(At, 0, 0); PG8_STAGE(PG8_SA(1, 1), a1 + hstep, voffA);
;             PG8_WAIT_V(8); PG8_WAIT_L(0); PG8_BAR; PG8_MMA(0, 0, At, B0); PG8_MMA(0, 1, At, B1); PG8_BAR; PG8_SCHED;
;             PG8_LDA(At, 0, 1); PG8_STAGE(PG8_SB(0, 0), b2, voffB); PG8_STAGE(PG8_SB(0, 1), b2 + hstep, voffB); PG8_STAGE(PG8_SA(0, 0), a2, voffA);
;             PG8_WAIT_V(8); PG8_WAIT_L(0); PG8_BAR; PG8_MMA(1, 0, At, B0); PG8_MMA(1, 1, At, B1); PG8_BAR; PG8_SCHED;
;             PG8_LDB(B0, 1, 0); PG8_LDB(B1, 1, 1); PG8_SCHED; PG8_LDA(At, 1, 0); PG8_STAGE(PG8_SA(0, 1), a2 + hstep, voffA);
;             PG8_WAIT_V(8); PG8_WAIT_L(0); PG8_BAR; PG8_MMA(0, 0, At, B0); PG8_MMA(0, 1, At, B1); PG8_BAR; PG8_SCHED;
;             PG8_LDA(At, 1, 1); PG8_STAGE(PG8_SB(1, 0), b3, voffB); PG8_STAGE(PG8_SB(1, 1), b3 + hstep, voffB); PG8_STAGE(PG8_SA(1, 0), a3, voffA);
;             PG8_WAIT_V(8); PG8_WAIT_L(0); PG8_BAR; PG8_MMA(1, 0, At, B0); PG8_MMA(1, 1, At, B1); PG8_BAR; PG8_SCHED;
	s_setprio 1
	s_waitcnt lgkmcnt(0)
	v_mfma_f32_16x16x32_bf16 v[60:63], v[136:139], v[180:183], v[60:63]
	v_mfma_f32_16x16x32_bf16 v[56:59], v[152:155], v[180:183], v[56:59]
	v_mfma_f32_16x16x32_bf16 v[48:51], v[136:139], v[188:191], v[48:51]
	v_mfma_f32_16x16x32_bf16 v[40:43], v[152:155], v[188:191], v[40:43]
	v_mfma_f32_16x16x32_bf16 v[32:35], v[136:139], v[196:199], v[32:35]
	v_mfma_f32_16x16x32_bf16 v[24:27], v[152:155], v[196:199], v[24:27]
	v_mfma_f32_16x16x32_bf16 v[16:19], v[136:139], v[204:207], v[16:19]
	v_mfma_f32_16x16x32_bf16 v[8:11], v[152:155], v[204:207], v[8:11]
	v_mfma_f32_16x16x32_bf16 v[60:63], v[148:151], v[184:187], v[60:63]
	v_mfma_f32_16x16x32_bf16 v[56:59], v[156:159], v[184:187], v[56:59]
	v_mfma_f32_16x16x32_bf16 v[48:51], v[148:151], v[192:195], v[48:51]
	v_mfma_f32_16x16x32_bf16 v[40:43], v[156:159], v[192:195], v[40:43]
	v_mfma_f32_16x16x32_bf16 v[32:35], v[148:151], v[200:203], v[32:35]
	v_mfma_f32_16x16x32_bf16 v[24:27], v[156:159], v[200:203], v[24:27]
	v_mfma_f32_16x16x32_bf16 v[16:19], v[148:151], v[208:211], v[16:19]
	v_mfma_f32_16x16x32_bf16 v[8:11], v[156:159], v[208:211], v[8:11]
	s_setprio 0
	s_setprio 1
	v_mfma_f32_16x16x32_bf16 v[52:55], v[160:163], v[180:183], v[52:55]
	v_mfma_f32_16x16x32_bf16 v[44:47], v[168:171], v[180:183], v[44:47]
	v_mfma_f32_16x16x32_bf16 v[36:39], v[160:163], v[188:191], v[36:39]
	v_mfma_f32_16x16x32_bf16 v[28:31], v[168:171], v[188:191], v[28:31]
	v_mfma_f32_16x16x32_bf16 v[20:23], v[160:163], v[196:199], v[20:23]
	v_mfma_f32_16x16x32_bf16 v[12:15], v[168:171], v[196:199], v[12:15]
	v_mfma_f32_16x16x32_bf16 v[4:7], v[160:163], v[204:207], v[4:7]
	v_mfma_f32_16x16x32_bf16 v[0:3], v[168:171], v[204:207], v[0:3]
	v_mfma_f32_16x16x32_bf16 v[52:55], v[164:167], v[184:187], v[52:55]
	v_mfma_f32_16x16x32_bf16 v[44:47], v[172:175], v[184:187], v[44:47]
	v_mfma_f32_16x16x32_bf16 v[36:39], v[164:167], v[192:195], v[36:39]
	v_mfma_f32_16x16x32_bf16 v[28:31], v[172:175], v[192:195], v[28:31]
	v_mfma_f32_16x16x32_bf16 v[20:23], v[164:167], v[200:203], v[20:23]
	v_mfma_f32_16x16x32_bf16 v[12:15], v[172:175], v[200:203], v[12:15]
	v_mfma_f32_16x16x32_bf16 v[4:7], v[164:167], v[208:211], v[4:7]
	v_mfma_f32_16x16x32_bf16 v[0:3], v[172:175], v[208:211], v[0:3]
	s_setprio 0
	s_barrier
	s_add_i32 s3, 0, 0x18000
	v_add_u32_e32 v147, s3, v141
	s_add_i32 s33, 0, 0x1c000
	ds_read_b128 v[136:139], v147
	ds_read_b128 v[148:151], v147 offset:1024
	ds_read_b128 v[152:155], v147 offset:2048
	ds_read_b128 v[156:159], v147 offset:3072
	v_add_u32_e32 v147, s33, v141
	ds_read_b128 v[160:163], v147
	ds_read_b128 v[164:167], v147 offset:1024
	ds_read_b128 v[168:171], v147 offset:2048
	ds_read_b128 v[172:175], v147 offset:3072
	s_add_u32 s26, s26, 0xb0000
	s_addc_u32 s27, s27, 0
	s_mov_b32 m0, s39
	v_lshl_add_u64 v[220:221], s[26:27], 0, v[128:129]
	ds_read_b128 v[180:183], v145 offset:32768
	ds_read_b128 v[184:187], v145 offset:33792
	ds_read_b128 v[188:191], v145 offset:34816
	ds_read_b128 v[192:195], v145 offset:35840
	ds_read_b128 v[196:199], v145 offset:36864
	ds_read_b128 v[200:203], v145 offset:37888
	ds_read_b128 v[204:207], v145 offset:38912
	ds_read_b128 v[208:211], v145 offset:39936
	global_load_lds_dwordx4 v[220:221], off
	v_lshl_add_u64 v[220:221], s[26:27], 0, v[130:131]
	s_mov_b32 m0, s40
	s_nop 0
	global_load_lds_dwordx4 v[220:221], off
	s_waitcnt vmcnt(8)
	s_waitcnt lgkmcnt(0)
	s_barrier
	s_setprio 1
	s_waitcnt lgkmcnt(0)
	v_mfma_f32_16x16x32_bf16 v[124:127], v[136:139], v[180:183], v[124:127]
	v_mfma_f32_16x16x32_bf16 v[120:123], v[152:155], v[180:183], v[120:123]
	v_mfma_f32_16x16x32_bf16 v[112:115], v[136:139], v[188:191], v[112:115]
	v_mfma_f32_16x16x32_bf16 v[104:107], v[152:155], v[188:191], v[104:107]
	v_mfma_f32_16x16x32_bf16 v[96:99], v[136:139], v[196:199], v[96:99]
	v_mfma_f32_16x16x32_bf16 v[88:91], v[152:155], v[196:199], v[88:91]
	v_mfma_f32_16x16x32_bf16 v[80:83], v[136:139], v[204:207], v[80:83]
	v_mfma_f32_16x16x32_bf16 v[72:75], v[152:155], v[204:207], v[72:75]
	v_mfma_f32_16x16x32_bf16 v[124:127], v[148:151], v[184:187], v[124:127]
	v_mfma_f32_16x16x32_bf16 v[120:123], v[156:159], v[184:187], v[120:123]
	v_mfma_f32_16x16x32_bf16 v[112:115], v[148:151], v[192:195], v[112:115]
	v_mfma_f32_16x16x32_bf16 v[104:107], v[156:159], v[192:195], v[104:107]
	v_mfma_f32_16x16x32_bf16 v[96:99], v[148:151], v[200:203], v[96:99]
	v_mfma_f32_16x16x32_bf16 v[88:91], v[156:159], v[200:203], v[88:91]
	v_mfma_f32_16x16x32_bf16 v[80:83], v[148:151], v[208:211], v[80:83]
	v_mfma_f32_16x16x32_bf16 v[72:75], v[156:159], v[208:211], v[72:75]
	s_setprio 0
	s_setprio 1
	v_mfma_f32_16x16x32_bf16 v[116:119], v[160:163], v[180:183], v[116:119]
	v_mfma_f32_16x16x32_bf16 v[108:111], v[168:171], v[180:183], v[108:111]
	v_mfma_f32_16x16x32_bf16 v[100:103], v[160:163], v[188:191], v[100:103]
	v_mfma_f32_16x16x32_bf16 v[92:95], v[168:171], v[188:191], v[92:95]
	v_mfma_f32_16x16x32_bf16 v[84:87], v[160:163], v[196:199], v[84:87]
	v_mfma_f32_16x16x32_bf16 v[76:79], v[168:171], v[196:199], v[76:79]
	v_mfma_f32_16x16x32_bf16 v[68:71], v[160:163], v[204:207], v[68:71]
	v_mfma_f32_16x16x32_bf16 v[64:67], v[168:171], v[204:207], v[64:67]
	v_mfma_f32_16x16x32_bf16 v[116:119], v[164:167], v[184:187], v[116:119]
	v_mfma_f32_16x16x32_bf16 v[108:111], v[172:175], v[184:187], v[108:111]
	v_mfma_f32_16x16x32_bf16 v[100:103], v[164:167], v[192:195], v[100:103]
	v_mfma_f32_16x16x32_bf16 v[92:95], v[172:175], v[192:195], v[92:95]
	v_mfma_f32_16x16x32_bf16 v[84:87], v[164:167], v[200:203], v[84:87]
	v_mfma_f32_16x16x32_bf16 v[76:79], v[172:175], v[200:203], v[76:79]
	v_mfma_f32_16x16x32_bf16 v[68:71], v[164:167], v[208:211], v[68:71]
	v_mfma_f32_16x16x32_bf16 v[64:67], v[172:175], v[208:211], v[64:67]
	s_setprio 0
	s_barrier
; #define PG8_STAGE(bufoff, gbase, voff) do { _Pragma("unroll") for (int _i = 0; _i < 2; ++_i) \
;         __builtin_amdgcn_global_load_lds((const unsigned*)((const char*)(gbase) + (voff)[_i]), (PG8_LAS unsigned*)(lds + (bufoff) + ldsw + _i * 8192), 16, 0, 0); } while (0)
; #define PG8_LDA(dst, b, h) do { _Pragma("unroll") for (int m = 0; m < 4; ++m) _Pragma("unroll") for (int k = 0; k < 2; ++k) dst[m][k] = *(const PG8_LAS bf16x8*)(lds + PG8_SA(b, h) + aoff + m * 2048 + k * 1024); } while (0)
; #define PG8_LDB(dst, b, h) do { _Pragma("unroll") for (int n = 0; n < 2; ++n) _Pragma("unroll") for (int k = 0; k < 2; ++k) dst[n][k] = *(const PG8_LAS bf16x8*)(lds + PG8_SB(b, h) + boff + n * 2048 + k * 1024); } while (0)
; #define PG8_MMA(ai, bj, At, Bt) do { __builtin_amdgcn_s_setprio(1); _Pragma("unroll") for (int m = 0; m < 4; ++m) _Pragma("unroll") for (int n = 0; n < 2; ++n) _Pragma("unroll") for (int k = 0; k < 2; ++k) \
;         acc[ai][bj][m][n] = __builtin_amdgcn_mfma_f32_16x16x32_bf16(Bt[n][k], At[m][k], acc[ai][bj][m][n], 0, 0, 0); __builtin_amdgcn_s_setprio(0); } while (0)
; #define PG8_WAIT_V(n) asm volatile("s_waitcnt vmcnt(" #n ")" ::: "memory")
; template <class Epi, class Sched, bool ALIGN_EPI = false, bool SP2 = false>
; __device__ __forceinline__ void gemm_phase(PG8_LAS unsigned char* lds, const Gemm g, const Sched& S, const Epi& E) {
;     ...
;             PG8_LDB(B0, 0, 0); PG8_LDB(B1, 0, 1); PG8_SCHED; PG8_LDA(At, 0, 0); PG8_STAGE(PG8_SA(1, 1), a1 + hstep, voffA);
;             PG8_WAIT_V(8); PG8_WAIT_L(0); PG8_BAR; PG8_MMA(0, 0, At, B0); PG8_MMA(0, 1, At, B1); PG8_BAR; PG8_SCHED;
;             PG8_LDA(At, 0, 1); PG8_STAGE(PG8_SB(0, 0), b2, voffB); PG8_STAGE(PG8_SB(0, 1), b2 + hstep, voffB); PG8_STAGE(PG8_SA(0, 0), a2, voffA);
;             PG8_WAIT_V(8); PG8_WAIT_L(0); PG8_BAR; PG8_MMA(1, 0, At, B0); PG8_MMA(1, 1, At, B1); PG8_BAR; PG8_SCHED;
;             PG8_LDB(B0, 1, 0); PG8_LDB(B1, 1, 1); PG8_SCHED; PG8_LDA(At, 1, 0); PG8_STAGE(PG8_SA(0, 1), a2 + hstep, voffA);
;             PG8_WAIT_V(8); PG8_WAIT_L(0); PG8_BAR; PG8_MMA(0, 0, At, B0); PG8_MMA(0, 1, At, B1); PG8_BAR; PG8_SCHED;
;             PG8_LDA(At, 1, 1); PG8_STAGE(PG8_SB(1, 0), b3, voffB); PG8_STAGE(PG8_SB(1, 1), b3 + hstep, voffB); PG8_STAGE(PG8_SA(1, 0), a3, voffA);
;             PG8_WAIT_V(8); PG8_WAIT_L(0); PG8_BAR; PG8_MMA(1, 0, At, B0); PG8_MMA(1, 1, At, B1); PG8_BAR; PG8_SCHED;
	s_add_i32 s3, s3, s36
	v_lshl_add_u64 v[212:213], v[212:213], 0, s[16:17]
	s_mov_b32 m0, s3
	ds_read_b128 v[180:183], v145 offset:49152
	ds_read_b128 v[184:187], v145 offset:50176
	ds_read_b128 v[188:191], v145 offset:51200
	ds_read_b128 v[192:195], v145 offset:52224
	ds_read_b128 v[196:199], v145 offset:53248
	ds_read_b128 v[200:203], v145 offset:54272
	ds_read_b128 v[204:207], v145 offset:55296
	ds_read_b128 v[208:211], v145 offset:56320
	global_load_lds_dwordx4 v[212:213], off
	s_add_i32 m0, s3, 0x2000
	s_add_u32 s24, s24, 0xb0080
	v_lshl_add_u64 v[212:213], v[214:215], 0, s[16:17]
	s_addc_u32 s25, s25, 0
	s_add_i32 s3, s33, s36
	global_load_lds_dwordx4 v[212:213], off
	v_lshl_add_u64 v[212:213], s[24:25], 0, v[128:129]
	s_mov_b32 m0, s3
	s_nop 0
	global_load_lds_dwordx4 v[212:213], off
	v_lshl_add_u64 v[212:213], s[24:25], 0, v[130:131]
	s_add_i32 m0, s3, 0x2000
	s_nop 0
	global_load_lds_dwordx4 v[212:213], off
	v_lshl_add_u64 v[212:213], v[216:217], 0, s[16:17]
	s_mov_b32 m0, s41
	s_nop 0
	global_load_lds_dwordx4 v[212:213], off
	v_lshl_add_u64 v[212:213], v[218:219], 0, s[16:17]
	s_mov_b32 m0, s42
	s_nop 0
	global_load_lds_dwordx4 v[212:213], off
	s_waitcnt vmcnt(8)
	s_waitcnt lgkmcnt(0)
	s_barrier
	s_setprio 1
	s_waitcnt lgkmcnt(0)
	v_mfma_f32_16x16x32_bf16 v[60:63], v[136:139], v[180:183], v[60:63]
	v_mfma_f32_16x16x32_bf16 v[56:59], v[152:155], v[180:183], v[56:59]
	v_mfma_f32_16x16x32_bf16 v[48:51], v[136:139], v[188:191], v[48:51]
	v_mfma_f32_16x16x32_bf16 v[40:43], v[152:155], v[188:191], v[40:43]
	v_mfma_f32_16x16x32_bf16 v[32:35], v[136:139], v[196:199], v[32:35]
	v_mfma_f32_16x16x32_bf16 v[24:27], v[152:155], v[196:199], v[24:27]
	v_mfma_f32_16x16x32_bf16 v[16:19], v[136:139], v[204:207], v[16:19]
	v_mfma_f32_16x16x32_bf16 v[8:11], v[152:155], v[204:207], v[8:11]
	v_mfma_f32_16x16x32_bf16 v[60:63], v[148:151], v[184:187], v[60:63]
	v_mfma_f32_16x16x32_bf16 v[56:59], v[156:159], v[184:187], v[56:59]
	v_mfma_f32_16x16x32_bf16 v[48:51], v[148:151], v[192:195], v[48:51]
	v_mfma_f32_16x16x32_bf16 v[40:43], v[156:159], v[192:195], v[40:43]
	v_mfma_f32_16x16x32_bf16 v[32:35], v[148:151], v[200:203], v[32:35]
	v_mfma_f32_16x16x32_bf16 v[24:27], v[156:159], v[200:203], v[24:27]
	v_mfma_f32_16x16x32_bf16 v[16:19], v[148:151], v[208:211], v[16:19]
	v_mfma_f32_16x16x32_bf16 v[8:11], v[156:159], v[208:211], v[8:11]
	s_setprio 0
	s_setprio 1
	v_mfma_f32_16x16x32_bf16 v[52:55], v[160:163], v[180:183], v[52:55]
	v_mfma_f32_16x16x32_bf16 v[44:47], v[168:171], v[180:183], v[44:47]
	v_mfma_f32_16x16x32_bf16 v[36:39], v[160:163], v[188:191], v[36:39]
	v_mfma_f32_16x16x32_bf16 v[28:31], v[168:171], v[188:191], v[28:31]
	v_mfma_f32_16x16x32_bf16 v[20:23], v[160:163], v[196:199], v[20:23]
	v_mfma_f32_16x16x32_bf16 v[12:15], v[168:171], v[196:199], v[12:15]
	v_mfma_f32_16x16x32_bf16 v[4:7], v[160:163], v[204:207], v[4:7]
	v_mfma_f32_16x16x32_bf16 v[0:3], v[168:171], v[204:207], v[0:3]
	v_mfma_f32_16x16x32_bf16 v[52:55], v[164:167], v[184:187], v[52:55]
	v_mfma_f32_16x16x32_bf16 v[44:47], v[172:175], v[184:187], v[44:47]
	v_mfma_f32_16x16x32_bf16 v[36:39], v[164:167], v[192:195], v[36:39]
	v_mfma_f32_16x16x32_bf16 v[28:31], v[172:175], v[192:195], v[28:31]
	v_mfma_f32_16x16x32_bf16 v[20:23], v[164:167], v[200:203], v[20:23]
	v_mfma_f32_16x16x32_bf16 v[12:15], v[172:175], v[200:203], v[12:15]
	v_mfma_f32_16x16x32_bf16 v[4:7], v[164:167], v[208:211], v[4:7]
	v_mfma_f32_16x16x32_bf16 v[0:3], v[172:175], v[208:211], v[0:3]
	s_setprio 0
	s_barrier
	s_add_i32 s51, s51, 2
	s_add_u32 s22, s22, 0x100
	s_addc_u32 s23, s23, 0
	s_add_u32 s49, s49, 0x100
	s_addc_u32 s50, s50, 0
	s_cmp_gt_u32 s51, 19
	s_cbranch_scc0 .LBB0_1440
; #define PG8_BAR __builtin_amdgcn_s_barrier()
; #define GEMM_N1024(EPI, Aoff, Woff, Mrows, Kdim, rowbase, Gn, cid, ...) do { pg8::Gemm g{(const bf16_t*)(a.ws + (Aoff)) + (size_t)(rowbase) * (Kdim), (const bf16_t*)(a.ws + (Woff)), (Mrows), 1024, (Kdim)}; \
;         pg8::StaticOrder S; S.init((Mrows), 1024, (Gn), (cid)); EPI E{__VA_ARGS__, (rowbase)}; pg8::gemm_phase<EPI, pg8::StaticOrder, false, true>(lds, g, S, E); } while (0)
; template <class Epi, class Sched, bool ALIGN_EPI = false, bool SP2 = false>
; __device__ __forceinline__ void gemm_phase(PG8_LAS unsigned char* lds, const Gemm g, const Sched& S, const Epi& E) {
;     ...
;         if constexpr (ALIGN_EPI) { if (wr == 0) PG8_BAR; }
;         if constexpr (!Epi::AFTER_DRAIN) { E(acc, cur, wr, wc, fr, fq); S.done(cur); }
;         if (!has_next) break;
; __global__ void __launch_bounds__(512) fwd_kernel(Args a) {
;     ...
;         if (G >= 32 && bx < 16) GEMM_N1024(EpiN1024<2>, A_HID, WS_WDN, MS, DFF, MP, 16, bx, (bf16_t*)(a.ws + A_GA), nullptr, (float*)(a.ws + WS_RSS2));
	s_and_b32 s100, s2, 15
	v_readfirstlane_b32 s101, v178
	s_lshl_b32 s98, s100, 18
	s_lshr_b32 s101, s101, 6
	s_lshl_b32 s99, s101, 15
	s_add_u32 s98, s98, s99
	s_lshl_b32 s100, s100, 2
	s_add_u32 s98, s54, s98
	s_addc_u32 s99, s55, 0
	s_add_u32 s98, s98, 0x9a00000
	s_addc_u32 s99, s99, 0
	s_add_u32 s100, s54, s100
	s_addc_u32 s101, s55, 0
	s_add_u32 s100, s100, 0x22a2000
	s_addc_u32 s101, s101, 0
	v_lshlrev_b32_e32 v160, 4, v176
	v_mov_b32_e32 v161, 0
	s_cmp_lt_u32 s2, 16
	s_cbranch_scc1 .Lsk_reader
	global_store_dwordx4 v160, v[0:3], s[98:99] sc1
	s_add_u32 s98, s98, 0x400
	s_addc_u32 s99, s99, 0
	global_store_dwordx4 v160, v[4:7], s[98:99] sc1
	s_add_u32 s98, s98, 0x400
	s_addc_u32 s99, s99, 0
	global_store_dwordx4 v160, v[8:11], s[98:99] sc1
	s_add_u32 s98, s98, 0x400
	s_addc_u32 s99, s99, 0
	global_store_dwordx4 v160, v[12:15], s[98:99] sc1
	s_add_u32 s98, s98, 0x400
	s_addc_u32 s99, s99, 0
	global_store_dwordx4 v160, v[16:19], s[98:99] sc1
	s_add_u32 s98, s98, 0x400
	s_addc_u32 s99, s99, 0
	global_store_dwordx4 v160, v[20:23], s[98:99] sc1
	s_add_u32 s98, s98, 0x400
	s_addc_u32 s99, s99, 0
	global_store_dwordx4 v160, v[24:27], s[98:99] sc1
	s_add_u32 s98, s98, 0x400
	s_addc_u32 s99, s99, 0
	global_store_dwordx4 v160, v[28:31], s[98:99] sc1
	s_add_u32 s98, s98, 0x400
	s_addc_u32 s99, s99, 0
	global_store_dwordx4 v160, v[32:35], s[98:99] sc1
	s_add_u32 s98, s98, 0x400
	s_addc_u32 s99, s99, 0
	global_store_dwordx4 v160, v[36:39], s[98:99] sc1
	s_add_u32 s98, s98, 0x400
	s_addc_u32 s99, s99, 0
	global_store_dwordx4 v160, v[40:43], s[98:99] sc1
	s_add_u32 s98, s98, 0x400
	s_addc_u32 s99, s99, 0
	global_store_dwordx4 v160, v[44:47], s[98:99] sc1
	s_add_u32 s98, s98, 0x400
	s_addc_u32 s99, s99, 0
	global_store_dwordx4 v160, v[48:51], s[98:99] sc1
	s_add_u32 s98, s98, 0x400
	s_addc_u32 s99, s99, 0
	global_store_dwordx4 v160, v[52:55], s[98:99] sc1
	s_add_u32 s98, s98, 0x400
	s_addc_u32 s99, s99, 0
	global_store_dwordx4 v160, v[56:59], s[98:99] sc1
	s_add_u32 s98, s98, 0x400
	s_addc_u32 s99, s99, 0
	global_store_dwordx4 v160, v[60:63], s[98:99] sc1
	s_add_u32 s98, s98, 0x400
	s_addc_u32 s99, s99, 0
	global_store_dwordx4 v160, v[64:67], s[98:99] sc1
	s_add_u32 s98, s98, 0x400
	s_addc_u32 s99, s99, 0
	global_store_dwordx4 v160, v[68:71], s[98:99] sc1
	s_add_u32 s98, s98, 0x400
	s_addc_u32 s99, s99, 0
	global_store_dwordx4 v160, v[72:75], s[98:99] sc1
	s_add_u32 s98, s98, 0x400
	s_addc_u32 s99, s99, 0
	global_store_dwordx4 v160, v[76:79], s[98:99] sc1
	s_add_u32 s98, s98, 0x400
	s_addc_u32 s99, s99, 0
	global_store_dwordx4 v160, v[80:83], s[98:99] sc1
	s_add_u32 s98, s98, 0x400
	s_addc_u32 s99, s99, 0
	global_store_dwordx4 v160, v[84:87], s[98:99] sc1
	s_add_u32 s98, s98, 0x400
	s_addc_u32 s99, s99, 0
	global_store_dwordx4 v160, v[88:91], s[98:99] sc1
	s_add_u32 s98, s98, 0x400
	s_addc_u32 s99, s99, 0
	global_store_dwordx4 v160, v[92:95], s[98:99] sc1
	s_add_u32 s98, s98, 0x400
	s_addc_u32 s99, s99, 0
	global_store_dwordx4 v160, v[96:99], s[98:99] sc1
	s_add_u32 s98, s98, 0x400
	s_addc_u32 s99, s99, 0
	global_store_dwordx4 v160, v[100:103], s[98:99] sc1
	s_add_u32 s98, s98, 0x400
	s_addc_u32 s99, s99, 0
	global_store_dwordx4 v160, v[104:107], s[98:99] sc1
	s_add_u32 s98, s98, 0x400
	s_addc_u32 s99, s99, 0
	global_store_dwordx4 v160, v[108:111], s[98:99] sc1
	s_add_u32 s98, s98, 0x400
	s_addc_u32 s99, s99, 0
	global_store_dwordx4 v160, v[112:115], s[98:99] sc1
	s_add_u32 s98, s98, 0x400
	s_addc_u32 s99, s99, 0
	global_store_dwordx4 v160, v[116:119], s[98:99] sc1
	s_add_u32 s98, s98, 0x400
	s_addc_u32 s99, s99, 0
	global_store_dwordx4 v160, v[120:123], s[98:99] sc1
	s_add_u32 s98, s98, 0x400
	s_addc_u32 s99, s99, 0
	global_store_dwordx4 v160, v[124:127], s[98:99] sc1
	s_add_u32 s98, s98, 0x400
	s_addc_u32 s99, s99, 0
	s_branch .LBB0_1428

; #define GEMM_N1024(EPI, Aoff, Woff, Mrows, Kdim, rowbase, Gn, cid, ...) do { pg8::Gemm g{(const bf16_t*)(a.ws + (Aoff)) + (size_t)(rowbase) * (Kdim), (const bf16_t*)(a.ws + (Woff)), (Mrows), 1024, (Kdim)}; \
;         pg8::StaticOrder S; S.init((Mrows), 1024, (Gn), (cid)); EPI E{__VA_ARGS__, (rowbase)}; pg8::gemm_phase<EPI, pg8::StaticOrder, false, true>(lds, g, S, E); } while (0)
; __global__ void __launch_bounds__(512) fwd_kernel(Args a) {
;     ...
;         if (G >= 32 && bx < 16) GEMM_N1024(EpiN1024<2>, A_HID, WS_WDN, MS, DFF, MP, 16, bx, (bf16_t*)(a.ws + A_GA), nullptr, (float*)(a.ws + WS_RSS2));
.Lsk_go:
	global_load_dwordx4 v[180:183], v160, s[98:99] sc1
	s_add_u32 s98, s98, 0x400
	s_addc_u32 s99, s99, 0
	global_load_dwordx4 v[184:187], v160, s[98:99] sc1
	s_add_u32 s98, s98, 0x400
	s_addc_u32 s99, s99, 0
	global_load_dwordx4 v[188:191], v160, s[98:99] sc1
	s_add_u32 s98, s98, 0x400
	s_addc_u32 s99, s99, 0
	global_load_dwordx4 v[192:195], v160, s[98:99] sc1
	s_add_u32 s98, s98, 0x400
	s_addc_u32 s99, s99, 0
	global_load_dwordx4 v[196:199], v160, s[98:99] sc1
	s_add_u32 s98, s98, 0x400
	s_addc_u32 s99, s99, 0
	global_load_dwordx4 v[200:203], v160, s[98:99] sc1
	s_add_u32 s98, s98, 0x400
	s_addc_u32 s99, s99, 0
	global_load_dwordx4 v[204:207], v160, s[98:99] sc1
	s_add_u32 s98, s98, 0x400
	s_addc_u32 s99, s99, 0
	global_load_dwordx4 v[208:211], v160, s[98:99] sc1
	s_add_u32 s98, s98, 0x400
	s_addc_u32 s99, s99, 0
	global_load_dwordx4 v[212:215], v160, s[98:99] sc1
	s_add_u32 s98, s98, 0x400
	s_addc_u32 s99, s99, 0
	global_load_dwordx4 v[216:219], v160, s[98:99] sc1
	s_add_u32 s98, s98, 0x400
	s_addc_u32 s99, s99, 0
	global_load_dwordx4 v[220:223], v160, s[98:99] sc1
	s_add_u32 s98, s98, 0x400
	s_addc_u32 s99, s99, 0
	global_load_dwordx4 v[224:227], v160, s[98:99] sc1
	s_add_u32 s98, s98, 0x400
	s_addc_u32 s99, s99, 0
	global_load_dwordx4 v[228:231], v160, s[98:99] sc1
	s_add_u32 s98, s98, 0x400
	s_addc_u32 s99, s99, 0
	global_load_dwordx4 v[232:235], v160, s[98:99] sc1
	s_add_u32 s98, s98, 0x400
	s_addc_u32 s99, s99, 0
	global_load_dwordx4 v[236:239], v160, s[98:99] sc1
	s_add_u32 s98, s98, 0x400
	s_addc_u32 s99, s99, 0
	global_load_dwordx4 v[240:243], v160, s[98:99] sc1
	s_add_u32 s98, s98, 0x400
	s_addc_u32 s99, s99, 0
	s_waitcnt vmcnt(8)
	v_add_f32_e32 v0, v0, v180
	v_add_f32_e32 v1, v1, v181
	v_add_f32_e32 v2, v2, v182
	v_add_f32_e32 v3, v3, v183
	v_add_f32_e32 v4, v4, v184
	v_add_f32_e32 v5, v5, v185
	v_add_f32_e32 v6, v6, v186
	v_add_f32_e32 v7, v7, v187
	v_add_f32_e32 v8, v8, v188
	v_add_f32_e32 v9, v9, v189
	v_add_f32_e32 v10, v10, v190
	v_add_f32_e32 v11, v11, v191
	v_add_f32_e32 v12, v12, v192
	v_add_f32_e32 v13, v13, v193
	v_add_f32_e32 v14, v14, v194
	v_add_f32_e32 v15, v15, v195
	v_add_f32_e32 v16, v16, v196
	v_add_f32_e32 v17, v17, v197
	v_add_f32_e32 v18, v18, v198
	v_add_f32_e32 v19, v19, v199
	v_add_f32_e32 v20, v20, v200
	v_add_f32_e32 v21, v21, v201
	v_add_f32_e32 v22, v22, v202
	v_add_f32_e32 v23, v23, v203
	v_add_f32_e32 v24, v24, v204
	v_add_f32_e32 v25, v25, v205
	v_add_f32_e32 v26, v26, v206
	v_add_f32_e32 v27, v27, v207
	v_add_f32_e32 v28, v28, v208
	v_add_f32_e32 v29, v29, v209
	v_add_f32_e32 v30, v30, v210
	v_add_f32_e32 v31, v31, v211
	global_load_dwordx4 v[180:183], v160, s[98:99] sc1
	s_add_u32 s98, s98, 0x400
	s_addc_u32 s99, s99, 0
	global_load_dwordx4 v[184:187], v160, s[98:99] sc1
	s_add_u32 s98, s98, 0x400
	s_addc_u32 s99, s99, 0
	global_load_dwordx4 v[188:191], v160, s[98:99] sc1
	s_add_u32 s98, s98, 0x400
	s_addc_u32 s99, s99, 0
	global_load_dwordx4 v[192:195], v160, s[98:99] sc1
	s_add_u32 s98, s98, 0x400
	s_addc_u32 s99, s99, 0
	global_load_dwordx4 v[196:199], v160, s[98:99] sc1
	s_add_u32 s98, s98, 0x400
	s_addc_u32 s99, s99, 0
	global_load_dwordx4 v[200:203], v160, s[98:99] sc1
	s_add_u32 s98, s98, 0x400
	s_addc_u32 s99, s99, 0
	global_load_dwordx4 v[204:207], v160, s[98:99] sc1
	s_add_u32 s98, s98, 0x400
	s_addc_u32 s99, s99, 0
	global_load_dwordx4 v[208:211], v160, s[98:99] sc1
	s_add_u32 s98, s98, 0x400
	s_addc_u32 s99, s99, 0
	s_waitcnt vmcnt(8)
	v_add_f32_e32 v32, v32, v212
	v_add_f32_e32 v33, v33, v213
	v_add_f32_e32 v34, v34, v214
	v_add_f32_e32 v35, v35, v215
	v_add_f32_e32 v36, v36, v216
	v_add_f32_e32 v37, v37, v217
	v_add_f32_e32 v38, v38, v218
	v_add_f32_e32 v39, v39, v219
	v_add_f32_e32 v40, v40, v220
	v_add_f32_e32 v41, v41, v221
	v_add_f32_e32 v42, v42, v222
	v_add_f32_e32 v43, v43, v223
	v_add_f32_e32 v44, v44, v224
	v_add_f32_e32 v45, v45, v225
	v_add_f32_e32 v46, v46, v226
	v_add_f32_e32 v47, v47, v227
	v_add_f32_e32 v48, v48, v228
	v_add_f32_e32 v49, v49, v229
	v_add_f32_e32 v50, v50, v230
	v_add_f32_e32 v51, v51, v231
	v_add_f32_e32 v52, v52, v232
	v_add_f32_e32 v53, v53, v233
	v_add_f32_e32 v54, v54, v234
	v_add_f32_e32 v55, v55, v235
	v_add_f32_e32 v56, v56, v236
	v_add_f32_e32 v57, v57, v237
	v_add_f32_e32 v58, v58, v238
	v_add_f32_e32 v59, v59, v239
	v_add_f32_e32 v60, v60, v240
	v_add_f32_e32 v61, v61, v241
	v_add_f32_e32 v62, v62, v242
	v_add_f32_e32 v63, v63, v243
	global_load_dwordx4 v[212:215], v160, s[98:99] sc1
	s_add_u32 s98, s98, 0x400
	s_addc_u32 s99, s99, 0
	global_load_dwordx4 v[216:219], v160, s[98:99] sc1
	s_add_u32 s98, s98, 0x400
	s_addc_u32 s99, s99, 0
	global_load_dwordx4 v[220:223], v160, s[98:99] sc1
	s_add_u32 s98, s98, 0x400
	s_addc_u32 s99, s99, 0
	global_load_dwordx4 v[224:227], v160, s[98:99] sc1
	s_add_u32 s98, s98, 0x400
	s_addc_u32 s99, s99, 0
	global_load_dwordx4 v[228:231], v160, s[98:99] sc1
	s_add_u32 s98, s98, 0x400
	s_addc_u32 s99, s99, 0
	global_load_dwordx4 v[232:235], v160, s[98:99] sc1
	s_add_u32 s98, s98, 0x400
	s_addc_u32 s99, s99, 0
	global_load_dwordx4 v[236:239], v160, s[98:99] sc1
	s_add_u32 s98, s98, 0x400
	s_addc_u32 s99, s99, 0
	global_load_dwordx4 v[240:243], v160, s[98:99] sc1
	s_add_u32 s98, s98, 0x400
	s_addc_u32 s99, s99, 0
	s_waitcnt vmcnt(8)
; __device__ __forceinline__ u32x2 pk4(f32x4 v) { u32x2 w; w.x = cvt_pk_bf16(v[0], v[1]); w.y = cvt_pk_bf16(v[2], v[3]); return w; }
; __device__ __forceinline__ f32x4 up4(u32x2 w) { return (f32x4){bf_lo(w.x), bf_hi(w.x), bf_lo(w.y), bf_hi(w.y)}; }
;     __device__ __forceinline__ void operator()(const AccT& acc, const pg8::Unit& u, int wr, int wc, int fr, int fq) const {
;         const int col0 = u.pn * 256 + wc * 32 + 4 * fq, row0 = row_base + u.pm * 256 + wr * 64 + fr;
; #pragma unroll
;         for (int ai = 0; ai < 2; ++ai)
; #pragma unroll
;             for (int m = 0; m < 4; ++m) { const int row = row0 + ai * 128 + m * 16; float ss = 0.f;
; #pragma unroll
;                 for (int bj = 0; bj < 2; ++bj)
; #pragma unroll
;                     for (int n = 0; n < 2; ++n) { f32x4 v = acc[ai][bj][m][n]; const size_t idx = (size_t)row * 1024 + col0 + bj * 128 + n * 16;
;                         if (MODE == 0) v = v * up4(*(const u32x2*)(io + idx));
;                         else if (MODE == 1) v = up4(*(const u32x2*)(io + idx)) + up4(*(const u32x2*)(g2 + idx)) * v;
;                         else ss += (v[0] * v[0] + v[1] * v[1]) + (v[2] * v[2] + v[3] * v[3]);
;                         if (!DRYE || v[0] == 123.456f) *(u32x2*)(io + idx) = pk4(v); }
;                 if (MODE == 2 && !DRYE) { ss += __shfl_xor(ss, 16); ss += __shfl_xor(ss, 32); if (fq == 0) atomicAdd(rowss + row, ss); } }
	v_add_f32_e32 v64, v64, v180
	v_add_f32_e32 v65, v65, v181
	v_add_f32_e32 v66, v66, v182
	v_add_f32_e32 v67, v67, v183
	v_add_f32_e32 v68, v68, v184
	v_add_f32_e32 v69, v69, v185
	v_add_f32_e32 v70, v70, v186
	v_add_f32_e32 v71, v71, v187
	v_add_f32_e32 v72, v72, v188
	v_add_f32_e32 v73, v73, v189
	v_add_f32_e32 v74, v74, v190
	v_add_f32_e32 v75, v75, v191
	v_add_f32_e32 v76, v76, v192
	v_add_f32_e32 v77, v77, v193
	v_add_f32_e32 v78, v78, v194
	v_add_f32_e32 v79, v79, v195
	v_add_f32_e32 v80, v80, v196
	v_add_f32_e32 v81, v81, v197
	v_add_f32_e32 v82, v82, v198
	v_add_f32_e32 v83, v83, v199
	v_add_f32_e32 v84, v84, v200
	v_add_f32_e32 v85, v85, v201
	v_add_f32_e32 v86, v86, v202
	v_add_f32_e32 v87, v87, v203
	v_add_f32_e32 v88, v88, v204
	v_add_f32_e32 v89, v89, v205
	v_add_f32_e32 v90, v90, v206
	v_add_f32_e32 v91, v91, v207
	v_add_f32_e32 v92, v92, v208
	v_add_f32_e32 v93, v93, v209
	v_add_f32_e32 v94, v94, v210
	v_add_f32_e32 v95, v95, v211
	s_waitcnt vmcnt(0)
	v_add_f32_e32 v96, v96, v212
	v_add_f32_e32 v97, v97, v213
	v_add_f32_e32 v98, v98, v214
	v_add_f32_e32 v99, v99, v215
	v_add_f32_e32 v100, v100, v216
	v_add_f32_e32 v101, v101, v217
	v_add_f32_e32 v102, v102, v218
	v_add_f32_e32 v103, v103, v219
	v_add_f32_e32 v104, v104, v220
	v_add_f32_e32 v105, v105, v221
	v_add_f32_e32 v106, v106, v222
	v_add_f32_e32 v107, v107, v223
	v_add_f32_e32 v108, v108, v224
	v_add_f32_e32 v109, v109, v225
	v_add_f32_e32 v110, v110, v226
	v_add_f32_e32 v111, v111, v227
	v_add_f32_e32 v112, v112, v228
	v_add_f32_e32 v113, v113, v229
	v_add_f32_e32 v114, v114, v230
	v_add_f32_e32 v115, v115, v231
	v_add_f32_e32 v116, v116, v232
	v_add_f32_e32 v117, v117, v233
	v_add_f32_e32 v118, v118, v234
	v_add_f32_e32 v119, v119, v235
	v_add_f32_e32 v120, v120, v236
	v_add_f32_e32 v121, v121, v237
	v_add_f32_e32 v122, v122, v238
	v_add_f32_e32 v123, v123, v239
	v_add_f32_e32 v124, v124, v240
	v_add_f32_e32 v125, v125, v241
	v_add_f32_e32 v126, v126, v242
	v_add_f32_e32 v127, v127, v243
	v_and_b32_e32 v147, 64, v146
	v_xor_b32_e32 v139, 16, v146
	v_add_u32_e32 v147, 64, v147
	v_cmp_lt_i32_e32 vcc, v139, v147
	v_lshl_add_u32 v149, s47, 8, v140
	v_add_u32_e32 v138, 0x4000, v149
	v_cndmask_b32_e32 v139, v146, v139, vcc
	v_lshlrev_b32_e32 v148, 2, v139
	v_xor_b32_e32 v139, 32, v146
	v_cmp_lt_i32_e32 vcc, v139, v147
	v_lshl_or_b32 v136, s48, 8, v142
	v_mul_f32_e32 v152, v125, v125
	v_cndmask_b32_e32 v139, v146, v139, vcc
	v_lshlrev_b32_e32 v147, 2, v139
	v_ashrrev_i32_e32 v139, 31, v138
	v_lshlrev_b64 v[150:151], 11, v[138:139]
	v_mul_f32_e32 v153, v127, v127
	v_ashrrev_i32_e32 v137, 31, v136
	v_fmac_f32_e32 v152, v124, v124
	v_fmac_f32_e32 v153, v126, v126
	v_cvt_pk_bf16_f32 v124, v124, v125
	v_cvt_pk_bf16_f32 v125, v126, v127
	v_lshl_add_u64 v[126:127], s[10:11], 0, v[150:151]
	v_lshl_add_u64 v[126:127], v[136:137], 1, v[126:127]
	global_store_dwordx2 v[126:127], v[124:125], off
	v_mul_f32_e32 v124, v121, v121
	v_mul_f32_e32 v125, v123, v123
	v_fmac_f32_e32 v124, v120, v120
	v_fmac_f32_e32 v125, v122, v122
	v_add_f32_e32 v124, v124, v125
	v_cvt_pk_bf16_f32 v120, v120, v121
	v_mul_f32_e32 v121, v117, v117
	v_mul_f32_e32 v125, v119, v119
	v_add_f32_e32 v152, v152, v153
	v_fmac_f32_e32 v121, v116, v116
	v_fmac_f32_e32 v125, v118, v118
	v_add_f32_e32 v124, v152, v124
	v_add_f32_e32 v121, v121, v125
	v_add_f32_e32 v121, v124, v121
	v_mul_f32_e32 v124, v109, v109
	v_mul_f32_e32 v125, v111, v111
	v_fmac_f32_e32 v124, v108, v108
	v_fmac_f32_e32 v125, v110, v110
	v_add_f32_e32 v124, v124, v125
	v_add_f32_e32 v124, v121, v124
	ds_bpermute_b32 v125, v148, v124
	v_cvt_pk_bf16_f32 v121, v122, v123
	global_store_dwordx2 v[126:127], v[120:121], off offset:32
	v_cvt_pk_bf16_f32 v120, v116, v117
	v_cvt_pk_bf16_f32 v121, v118, v119
	s_waitcnt lgkmcnt(0)
	v_add_f32_e32 v116, v124, v125
	ds_bpermute_b32 v117, v147, v116
	v_cvt_pk_bf16_f32 v108, v108, v109
	v_cvt_pk_bf16_f32 v109, v110, v111
	global_store_dwordx2 v[126:127], v[120:121], off offset:256
	global_store_dwordx2 v[126:127], v[108:109], off offset:288
	s_and_saveexec_b64 s[22:23], s[0:1]
	s_cbranch_execz .LBB0_1443
	v_lshl_add_u64 v[108:109], v[138:139], 2, s[14:15]
	s_waitcnt lgkmcnt(0)
	v_add_f32_e32 v110, v116, v117
	global_atomic_add_f32 v[108:109], v110, off

; #define PG8_WAIT_V(n) asm volatile("s_waitcnt vmcnt(" #n ")" ::: "memory")
; #define PG8_BAR __builtin_amdgcn_s_barrier()
; template <class Epi, class Sched, bool ALIGN_EPI = false, bool SP2 = false>
; __device__ __forceinline__ void gemm_phase(PG8_LAS unsigned char* lds, const Gemm g, const Sched& S, const Epi& E) {
;     ...
;     PG8_WAIT_V(0);
;     if constexpr (!ALIGN_EPI) { if (wr == 0) PG8_BAR; }
;     PG8_BAR;
.LBB0_1459:
	s_barrier
	s_cmp_lt_u32 s2, 16
	s_cbranch_scc1 .Lsk_nowb
	v_cmp_eq_u32_e32 vcc, 0, v178
	s_and_saveexec_b64 s[0:1], vcc
	s_cbranch_execz .Lsk_wbj
	s_and_b32 s100, s2, 15
	s_lshl_b32 s100, s100, 2
	s_add_u32 s100, s54, s100
	s_addc_u32 s101, s55, 0
	s_add_u32 s100, s100, 0x22a2000
	s_addc_u32 s101, s101, 0
	v_mov_b32_e32 v161, 0
	v_mov_b32_e32 v162, 1
	global_atomic_add v161, v162, s[100:101] sc1
